# sample-attn: counted vmcnt per conversion batch instead of vmcnt(0) in P.C part and before barrier
# baseline (speedup 1.0000x reference)
.LBB0_1869:
	s_waitcnt lgkmcnt(0)
	ds_read2_b32 v[150:151], v208 offset0:32 offset1:48
	ds_read2_b32 v[148:149], v208 offset1:16
	s_waitcnt lgkmcnt(0)
	v_max_f32_e32 v146, v151, v151
	v_max_f32_e32 v147, v150, v150
	v_max_f32_e32 v146, v147, v146
	v_max3_f32 v146, v148, v149, v146
	s_nop 1
	v_mov_b32_dpp v147, v146 quad_perm:[1,0,3,2] row_mask:0xf bank_mask:0xf bound_ctrl:1
	v_max_f32_e32 v147, v147, v147
	v_max_f32_e32 v146, v146, v147
	s_nop 1
	v_mov_b32_dpp v147, v146 quad_perm:[2,3,0,1] row_mask:0xf bank_mask:0xf bound_ctrl:1
	v_max_f32_e32 v147, v147, v147
	v_max_f32_e32 v146, v146, v147
	s_nop 1
	v_mov_b32_dpp v147, v146 row_half_mirror row_mask:0xf bank_mask:0xf bound_ctrl:1
	v_max_f32_e32 v147, v147, v147
	v_max_f32_e32 v146, v146, v147
	s_nop 1
	v_mov_b32_dpp v147, v146 row_mirror row_mask:0xf bank_mask:0xf bound_ctrl:1
	v_max3_f32 v146, v213, v146, v147
	v_sub_f32_e32 v147, v148, v146
	v_exp_f32_e32 v147, v147
	v_sub_f32_e32 v148, v149, v146
	v_exp_f32_e32 v148, v148
	v_sub_f32_e32 v149, v150, v146
	v_bfe_u32 v150, v147, 16, 1
	v_exp_f32_e32 v149, v149
	v_add3_u32 v150, v147, v150, s74
	ds_write_b16_d16_hi v209, v150
	v_bfe_u32 v150, v148, 16, 1
	v_add3_u32 v150, v148, v150, s74
	ds_write_b16_d16_hi v209, v150 offset:32
	v_sub_f32_e32 v150, v151, v146
	v_bfe_u32 v153, v149, 16, 1
	v_exp_f32_e32 v150, v150
	v_sub_f32_e32 v152, v213, v146
	v_add3_u32 v151, v149, v153, s74
	ds_write_b16_d16_hi v209, v151 offset:64
	v_exp_f32_e32 v151, v152
	v_bfe_u32 v152, v150, 16, 1
	v_add3_u32 v152, v150, v152, s74
	ds_write_b16_d16_hi v209, v152 offset:96
	s_and_saveexec_b64 s[48:49], s[8:9]
	ds_write_b32 v210, v151
	s_or_b64 exec, exec, s[48:49]
	v_add_f32_e32 v147, 0, v147
	v_add_f32_e32 v147, v148, v147
	v_add_f32_e32 v147, v149, v147
	v_add_f32_e32 v148, v150, v147
	s_waitcnt lgkmcnt(0)
	v_add_u32_e32 v147, 0, v184
	s_barrier
	v_add_u32_e32 v147, 0x1cb00, v147
	v_fmac_f32_e32 v148, v212, v151
	ds_read_b128 v[150:153], v147
	s_lshr_b32 s81, s78, 3
	s_cmp_lg_u32 s47, 7
	s_cselect_b64 s[48:49], -1, 0
	s_and_b64 vcc, exec, s[48:49]
	s_waitcnt lgkmcnt(0)
	v_pk_mul_f32 v[134:135], v[134:135], v[150:151]
	v_pk_mul_f32 v[136:137], v[136:137], v[152:153]
	v_pk_mul_f32 v[142:143], v[142:143], v[150:151]
	v_pk_mul_f32 v[144:145], v[144:145], v[152:153]
	ds_read_b128 v[150:153], v147 offset:64
	s_waitcnt lgkmcnt(0)
	v_pk_mul_f32 v[130:131], v[130:131], v[150:151]
	v_pk_mul_f32 v[132:133], v[132:133], v[152:153]
	v_pk_mul_f32 v[138:139], v[138:139], v[150:151]
	v_pk_mul_f32 v[140:141], v[140:141], v[152:153]
	ds_read_b128 v[150:153], v211
	ds_read_b128 v[154:157], v211 offset:2304
	ds_read_b64_tr_b16 v[198:199], v186 offset:2112
	ds_read_b64_tr_b16 v[196:197], v186
	ds_read_b64_tr_b16 v[200:201], v186 offset:32
	ds_read_b64_tr_b16 v[202:203], v186 offset:2144
	s_waitcnt lgkmcnt(2)
	v_mfma_f32_16x16x32_bf16 v[134:137], v[150:153], v[196:199], v[134:137]
	v_mfma_f32_16x16x32_bf16 v[130:133], v[154:157], v[196:199], v[130:133]
	s_waitcnt lgkmcnt(0)
	v_mfma_f32_16x16x32_bf16 v[142:145], v[150:153], v[200:203], v[142:145]
	v_mfma_f32_16x16x32_bf16 v[138:141], v[154:157], v[200:203], v[138:141]
	ds_read_b128 v[150:153], v211 offset:64
	ds_read_b128 v[154:157], v211 offset:2368
	ds_read_b64_tr_b16 v[196:197], v186 offset:16896
	ds_read_b64_tr_b16 v[198:199], v186 offset:19008
	s_waitcnt lgkmcnt(0)
	v_mfma_f32_16x16x32_bf16 v[134:137], v[150:153], v[196:199], v[134:137]
	v_mfma_f32_16x16x32_bf16 v[130:133], v[154:157], v[196:199], v[130:133]
	ds_read_b64_tr_b16 v[196:197], v186 offset:16928
	ds_read_b64_tr_b16 v[198:199], v186 offset:19040
	s_waitcnt lgkmcnt(0)
	v_mfma_f32_16x16x32_bf16 v[142:145], v[150:153], v[196:199], v[142:145]
	v_mfma_f32_16x16x32_bf16 v[138:141], v[154:157], v[196:199], v[138:141]
	s_cbranch_vccnz .LBB0_1875
	s_mul_i32 s47, s81, s24
	s_add_i32 s50, s47, s25
	s_ashr_i32 s51, s50, 31
	s_lshl_b64 s[52:53], s[50:51], 15
	v_mov_b32_e32 v151, s53
	v_or_b32_e32 v150, s52, v168
	v_lshl_add_u64 v[152:153], v[162:163], 0, v[150:151]
	global_store_dword v[152:153], v134, off
	global_store_dword v[152:153], v135, off offset:1024
	global_store_dword v[152:153], v136, off offset:2048
	global_store_dword v[152:153], v137, off offset:3072
	global_store_dword v[152:153], v142, off offset:64
	global_store_dword v[152:153], v143, off offset:1088
	global_store_dword v[152:153], v144, off offset:2112
	global_store_dword v[152:153], v145, off offset:3136
	v_or_b32_e32 v152, 0x4000, v150
	v_mov_b32_e32 v153, s53
	v_lshl_add_u64 v[154:155], v[162:163], 0, v[152:153]
	global_store_dword v[154:155], v130, off
	v_or_b32_e32 v154, 0x4400, v150
	v_mov_b32_e32 v155, s53
	v_lshl_add_u64 v[156:157], v[162:163], 0, v[154:155]
	v_add_f32_dpp v147, v148, v148 quad_perm:[1,0,3,2] row_mask:0xf bank_mask:0xf bound_ctrl:1
	global_store_dword v[156:157], v131, off
	v_or_b32_e32 v156, 0x4800, v150
	v_mov_b32_e32 v157, s53
	v_lshl_add_u64 v[152:153], v[164:165], 0, v[152:153]
	v_add_f32_dpp v147, v147, v147 quad_perm:[2,3,0,1] row_mask:0xf bank_mask:0xf bound_ctrl:1
	v_lshl_add_u64 v[196:197], v[162:163], 0, v[156:157]
	v_or_b32_e32 v150, 0x4c00, v150
	global_store_dword v[152:153], v138, off
	v_lshl_add_u64 v[152:153], v[164:165], 0, v[154:155]
	v_add_f32_dpp v147, v147, v147 row_half_mirror row_mask:0xf bank_mask:0xf bound_ctrl:1
	global_store_dword v[196:197], v132, off
	v_lshl_add_u64 v[196:197], v[162:163], 0, v[150:151]
	global_store_dword v[152:153], v139, off
	v_lshl_add_u64 v[152:153], v[164:165], 0, v[156:157]
	v_lshl_add_u64 v[150:151], v[164:165], 0, v[150:151]
	v_mov_b32_dpp v149, v147 row_mirror row_mask:0xf bank_mask:0xf bound_ctrl:1
	global_store_dword v[196:197], v133, off
	global_store_dword v[152:153], v140, off
	global_store_dword v[150:151], v141, off
	s_and_saveexec_b64 s[52:53], s[8:9]
	s_cbranch_execz .LBB0_1874
	s_lshl_b64 s[50:51], s[50:51], 8
	v_lshl_add_u64 v[150:151], v[166:167], 0, s[50:51]
	v_add_f32_e32 v147, v147, v149
	global_store_dwordx2 v[150:151], v[146:147], off

.LBB0_1875:
	s_barrier
	s_waitcnt vmcnt(5)
	s_ashr_i32 s89, s46, 31
	s_mov_b32 s88, s46
	s_lshl_b64 s[88:89], s[88:89], 7
	s_lshl_b32 s90, s80, 6
	s_and_b32 s90, s90, 64
	s_or_b32 s88, s88, s90
	s_lshl_b64 s[90:91], s[88:89], 10
	s_lshl_b64 s[88:89], s[88:89], 7
	v_lshl_add_u64 v[204:205], v[158:159], 0, s[90:91]
	ds_read_b128 v[150:153], v169
	ds_read_b128 v[154:157], v169 offset:8192
	ds_read_b128 v[196:199], v169 offset:16384
	ds_read_b128 v[200:203], v169 offset:24576
	s_waitcnt lgkmcnt(3)
	v_cvt_pk_bf16_f32 v150, v150, v151
	v_cvt_pk_bf16_f32 v151, v152, v153
	ds_write_b64 v171, v[150:151]
	v_lshl_add_u64 v[214:215], v[204:205], 0, s[20:21]
	s_mov_b32 m0, s54
	s_nop 0
	global_load_lds_dwordx4 v[214:215], off
	s_waitcnt lgkmcnt(3)
	v_cvt_pk_bf16_f32 v150, v154, v155
	v_cvt_pk_bf16_f32 v151, v156, v157
	ds_write_b64 v171, v[150:151] offset:4224
	v_lshl_add_u64 v[214:215], v[204:205], 0, s[30:31]
	s_mov_b32 m0, s55
	s_nop 0
	global_load_lds_dwordx4 v[214:215], off
	s_waitcnt lgkmcnt(3)
	v_cvt_pk_bf16_f32 v150, v196, v197
	v_cvt_pk_bf16_f32 v151, v198, v199
	ds_write_b64 v171, v[150:151] offset:8448
	v_lshl_add_u64 v[214:215], v[204:205], 0, s[34:35]
	s_mov_b32 m0, s56
	s_nop 0
	global_load_lds_dwordx4 v[214:215], off
	s_waitcnt lgkmcnt(3)
	v_cvt_pk_bf16_f32 v150, v200, v201
	v_cvt_pk_bf16_f32 v151, v202, v203
	ds_write_b64 v171, v[150:151] offset:12672
	v_lshl_add_u64 v[214:215], v[204:205], 0, s[36:37]
	s_mov_b32 m0, s57
	s_nop 0
	global_load_lds_dwordx4 v[214:215], off
	s_waitcnt vmcnt(5)
	ds_read_b128 v[150:153], v169 offset:32768
	ds_read_b128 v[154:157], v169 offset:40960
	ds_read_b128 v[196:199], v169 offset:49152
	ds_read_b128 v[200:203], v169 offset:57344
	s_waitcnt lgkmcnt(3)
	v_cvt_pk_bf16_f32 v150, v150, v151
	v_cvt_pk_bf16_f32 v151, v152, v153
	ds_write_b64 v171, v[150:151] offset:16896
	v_lshl_add_u64 v[214:215], v[204:205], 0, s[38:39]
	s_mov_b32 m0, s58
	s_nop 0
	global_load_lds_dwordx4 v[214:215], off
	s_waitcnt lgkmcnt(3)
	v_cvt_pk_bf16_f32 v150, v154, v155
	v_cvt_pk_bf16_f32 v151, v156, v157
	ds_write_b64 v171, v[150:151] offset:21120
	v_lshl_add_u64 v[214:215], v[204:205], 0, s[40:41]
	s_mov_b32 m0, s59
	s_nop 0
	global_load_lds_dwordx4 v[214:215], off
	s_waitcnt lgkmcnt(3)
	v_cvt_pk_bf16_f32 v150, v196, v197
	v_cvt_pk_bf16_f32 v151, v198, v199
	ds_write_b64 v171, v[150:151] offset:25344
	v_lshl_add_u64 v[214:215], v[204:205], 0, s[42:43]
	s_mov_b32 m0, s60
	s_nop 0
	global_load_lds_dwordx4 v[214:215], off
	s_waitcnt lgkmcnt(3)
	v_cvt_pk_bf16_f32 v150, v200, v201
	v_cvt_pk_bf16_f32 v151, v202, v203
	ds_write_b64 v171, v[150:151] offset:29568
	v_lshl_add_u64 v[214:215], v[204:205], 0, s[44:45]
	s_mov_b32 m0, s61
	s_nop 0
	global_load_lds_dwordx4 v[214:215], off
	v_lshlrev_b32_e32 v237, 4, v230
	v_or_b32_e32 v237, 0x10000, v237
	s_waitcnt vmcnt(8)
	ds_read_b128 v[150:153], v237
	s_waitcnt lgkmcnt(0)
	v_cvt_pk_bf16_f32 v150, v150, v151
	v_cvt_pk_bf16_f32 v151, v152, v153
	ds_write_b64 v182, v[150:151]
	v_lshl_add_u64 v[214:215], v[160:161], 0, s[88:89]
	s_mov_b32 m0, s28
	v_and_b32_e32 v149, 0xffff0000, v150
	global_load_lds_dwordx4 v[214:215], off
	v_lshlrev_b32_e32 v147, 16, v150
	v_mul_f32_e32 v149, v149, v149
	v_fmac_f32_e32 v149, v147, v147
	v_and_b32_e32 v147, 0xffff0000, v151
	v_lshlrev_b32_e32 v150, 16, v151
	v_mul_f32_e32 v147, v147, v147
	v_fmac_f32_e32 v147, v150, v150
	v_add_f32_e32 v147, v149, v147
	s_nop 1
	v_add_f32_dpp v147, v147, v147 quad_perm:[1,0,3,2] row_mask:0xf bank_mask:0xf bound_ctrl:1
	s_nop 1
	v_add_f32_dpp v147, v147, v147 quad_perm:[2,3,0,1] row_mask:0xf bank_mask:0xf bound_ctrl:1
	s_nop 1
	v_mov_b32_dpp v149, v147 row_half_mirror row_mask:0xf bank_mask:0xf bound_ctrl:1
	s_and_saveexec_b64 s[50:51], s[2:3]
	v_add_f32_e32 v147, v147, v149
	ds_write_b32 v189, v147
	s_or_b64 exec, exec, s[50:51]
	s_add_i32 s78, s78, 1
	s_bitcmp1_b32 s78, 3
	s_cselect_b32 s92, 0x1800, 0
	s_and_saveexec_b64 s[86:87], s[84:85]
	v_add_u32_e32 v147, s92, v191
	s_waitcnt vmcnt(9)
	ds_write_b128 v147, v[178:181]
	s_mov_b64 exec, s[86:87]
	s_waitcnt lgkmcnt(0)
	s_barrier
	s_cmp_lg_u32 s78, s79
	s_cbranch_scc1 .LBB0_1863
